# v138 + attention no-mask exps batched after the last logits MFMAs (7 wait-state nops removed)
# baseline (speedup 1.0000x reference)
; #define LAS __attribute__((address_space(3)))
; __device__ __forceinline__ void attn_unit(LAS unsigned char* lds, const bf16_t* Qm, const bf16_t* Km, const bf16_t* VT, const bf16_t* GBm, bf16_t* YB, int b, int hp, int qb) {
;     ...
;         if (k0 < qw + 15 && !__all(Rs == 0.f)) {
;             f32x4 s[4];
; #pragma unroll
;             for (int rb = 0; rb < 4; ++rb) {
;                 const int c = rb >> 1, e = rb & 1;
;                 const int kl = 32 * c + (fr >> 2) * 8 + e * 4 + (fr & 3);
;                 s[rb] = (f32x4){0.f, 0.f, 0.f, 0.f};
; #pragma unroll
;                 for (int ks = 0; ks < 4; ++ks) {
;                     const bf16x8 a = *(const LAS bf16x8*)(KL + kl * 272 + (ks * 32 + fq * 8) * 2);
;                     s[rb] = __builtin_amdgcn_mfma_f32_16x16x32_bf16(a, qf[ks], s[rb], 0, 0, 0);
;                 }
;             }
;             const int qi = qw + fr;
;             float be[2][8], om[2][8];
; #pragma unroll
;             for (int c = 0; c < 2; ++c)
; #pragma unroll
;                 for (int i = 0; i < 8; ++i) {
;                     const float z = s[2 * c + (i >> 2)][i & 3];
;                     const int key = k0 + 32 * c + 8 * fq + i;
;                     const float e = __builtin_amdgcn_exp2f(-fabsf(z));
;                     const float r = __builtin_amdgcn_rcpf(1.0f + e);
;                     const bool pos = z >= 0.f, valid = key < qi;
;                     be[c][i] = valid ? (pos ? r : e * r) : 0.f;
;                     om[c][i] = valid ? (pos ? e * r : r) : 1.f;
;                 }
;             float suf[2][8], Gs[2], Tt[2];
; #pragma unroll
;             for (int c = 0; c < 2; ++c) {
;                 float run = 1.f;
; #pragma unroll
;                 for (int i = 7; i >= 0; --i) { suf[c][i] = run; run *= om[c][i]; }
;                 const float t1 = __shfl(run, (lane + 16) & 63), t2 = __shfl(run, (lane + 32) & 63), t3 = __shfl(run, (lane + 48) & 63);
;                 Gs[c] = (fq < 3 ? t1 : 1.f) * (fq < 2 ? t2 : 1.f) * (fq < 1 ? t3 : 1.f);
;                 Tt[c] = (run * t1) * (t2 * t3);
;             }
.Lattn_nomask:
	ds_read_b128 v[120:123], v116
	ds_read_b128 v[124:127], v116 offset:64
	ds_read_b128 v[128:131], v116 offset:1088
	ds_read_b128 v[132:135], v116 offset:1152
	s_waitcnt lgkmcnt(3)
	v_mfma_f32_16x16x32_bf16 v[120:123], v[120:123], v[0:3], 0
	s_waitcnt lgkmcnt(2)
	v_mfma_f32_16x16x32_bf16 v[120:123], v[124:127], v[4:7], v[120:123]
	ds_read_b128 v[124:127], v116 offset:128
	ds_read_b128 v[136:139], v116 offset:192
	s_waitcnt lgkmcnt(3)
	v_mfma_f32_16x16x32_bf16 v[128:131], v[128:131], v[0:3], 0
	s_waitcnt lgkmcnt(1)
	v_mfma_f32_16x16x32_bf16 v[120:123], v[124:127], v[8:11], v[120:123]
	ds_read_b128 v[124:127], v116 offset:1216
	ds_read_b128 v[140:143], v116 offset:1280
	ds_read_b128 v[144:147], v116 offset:8704
	ds_read_b128 v[148:151], v116 offset:8768
	v_mfma_f32_16x16x32_bf16 v[128:131], v[132:135], v[4:7], v[128:131]
	ds_read_b128 v[132:135], v116 offset:8832
	ds_read_b128 v[152:155], v116 offset:8896
	ds_read_b128 v[156:159], v116 offset:9792
	ds_read_b128 v[160:163], v116 offset:9856
	s_waitcnt lgkmcnt(8)
	v_mfma_f32_16x16x32_bf16 v[120:123], v[136:139], v[12:15], v[120:123]
	ds_read_b128 v[136:139], v116 offset:9920
	ds_read_b128 v[164:167], v116 offset:9984
	s_waitcnt lgkmcnt(9)
	v_mfma_f32_16x16x32_bf16 v[124:127], v[124:127], v[8:11], v[128:131]
	s_nop 3
	v_exp_f32_e32 v97, v120
	s_nop 0
	v_add_f32_e32 v101, 1.0, v97
	s_waitcnt lgkmcnt(7)
	v_mfma_f32_16x16x32_bf16 v[128:131], v[144:147], v[0:3], 0
	v_rcp_f32_e32 v168, v101
	s_nop 0
	v_mul_f32_e32 v101, v97, v168
	s_waitcnt lgkmcnt(6)
	v_mfma_f32_16x16x32_bf16 v[128:131], v[148:151], v[4:7], v[128:131]
	v_mfma_f32_16x16x32_bf16 v[124:127], v[140:143], v[12:15], v[124:127]
	v_exp_f32_e32 v142, v121
	v_exp_f32_e32 v143, v122
	s_waitcnt lgkmcnt(5)
	v_mfma_f32_16x16x32_bf16 v[128:131], v[132:135], v[8:11], v[128:131]
	v_add_f32_e32 v103, 1.0, v142
	v_rcp_f32_e32 v103, v103
	s_waitcnt lgkmcnt(3)
	v_mfma_f32_16x16x32_bf16 v[132:135], v[156:159], v[0:3], 0
	v_add_f32_e32 v120, 1.0, v143
	v_rcp_f32_e32 v120, v120
	s_waitcnt lgkmcnt(2)
	v_mfma_f32_16x16x32_bf16 v[132:135], v[160:163], v[4:7], v[132:135]
	s_waitcnt lgkmcnt(1)
	v_mfma_f32_16x16x32_bf16 v[132:135], v[136:139], v[8:11], v[132:135]
	v_exp_f32_e32 v144, v123
	v_exp_f32_e32 v145, v124
	v_add_f32_e32 v121, 1.0, v144
	v_rcp_f32_e32 v121, v121
	v_add_f32_e32 v122, 1.0, v145
	v_rcp_f32_e32 v122, v122
	v_mfma_f32_16x16x32_bf16 v[128:131], v[152:155], v[12:15], v[128:131]
	v_exp_f32_e32 v146, v125
	v_exp_f32_e32 v126, v126
	v_exp_f32_e32 v127, v127
	s_waitcnt lgkmcnt(0)
	v_mfma_f32_16x16x32_bf16 v[132:135], v[164:167], v[12:15], v[132:135]
	v_add_f32_e32 v123, 1.0, v146
	v_add_f32_e32 v124, 1.0, v126
	v_add_f32_e32 v125, 1.0, v127
	v_rcp_f32_e32 v123, v123
	v_rcp_f32_e32 v124, v124
	v_rcp_f32_e32 v147, v125
	v_exp_f32_e32 v138, v128
	v_exp_f32_e32 v131, v131
	v_add_f32_e32 v136, 1.0, v138
	v_rcp_f32_e32 v140, v136
	v_exp_f32_e32 v129, v129
	v_exp_f32_e32 v130, v130
	v_mul_f32_e32 v128, v138, v140
	v_add_f32_e32 v125, 1.0, v129
	v_add_f32_e32 v136, 1.0, v130
	v_add_f32_e32 v137, 1.0, v131
	v_rcp_f32_e32 v125, v125
	v_rcp_f32_e32 v141, v136
	v_rcp_f32_e32 v148, v137
	v_mul_f32_e32 v153, v147, v124
	v_mul_f32_e32 v154, v123, v153
	v_mul_f32_e32 v155, v122, v154
	v_exp_f32_e32 v132, v132
	v_exp_f32_e32 v133, v133
	v_exp_f32_e32 v134, v134
	v_exp_f32_e32 v99, v135
	v_mul_f32_e32 v156, v121, v155
	v_add_f32_e32 v136, 1.0, v132
	v_add_f32_e32 v137, 1.0, v133
	v_add_f32_e32 v138, 1.0, v134
	v_add_f32_e32 v139, 1.0, v99
	v_rcp_f32_e32 v149, v136
	v_rcp_f32_e32 v150, v137
	v_rcp_f32_e32 v152, v138
	v_rcp_f32_e32 v151, v139
	v_mul_f32_e32 v157, v120, v156
	v_mul_f32_e32 v103, v103, v157
	v_mul_f32_e32 v136, v168, v103
	v_or_b32_e32 v135, v105, v107
	v_lshlrev_b32_e32 v135, 2, v135
	v_xor_b32_e32 v135, 0x80, v135
	v_mul_f32_e32 v152, v151, v152
	ds_bpermute_b32 v137, v135, v136
	ds_bpermute_b32 v138, v118, v136
	v_mul_f32_e32 v150, v150, v152
	v_mul_f32_e32 v149, v149, v150
	v_mul_f32_e32 v148, v148, v149
	v_mul_f32_e32 v158, v141, v148
	v_mul_f32_e32 v159, v125, v158
	ds_bpermute_b32 v139, v119, v136
	s_waitcnt lgkmcnt(2)
	v_cndmask_b32_e64 v97, 1.0, v137, s[10:11]
	s_waitcnt lgkmcnt(1)
; #define LAS __attribute__((address_space(3)))
; __device__ __forceinline__ unsigned cvt_pk_bf16(float lo, float hi) { unsigned r; asm volatile("v_cvt_pk_bf16_f32 %0, %1, %2" : "=v"(r) : "v"(lo), "v"(hi)); return r; }
; __device__ __forceinline__ void attn_unit(LAS unsigned char* lds, const bf16_t* Qm, const bf16_t* Km, const bf16_t* VT, const bf16_t* GBm, bf16_t* YB, int b, int hp, int qb) {
;     ...
;                 const float t1 = __shfl(run, (lane + 16) & 63), t2 = __shfl(run, (lane + 32) & 63), t3 = __shfl(run, (lane + 48) & 63);
;                 Gs[c] = (fq < 3 ? t1 : 1.f) * (fq < 2 ? t2 : 1.f) * (fq < 1 ? t3 : 1.f);
;                 Tt[c] = (run * t1) * (t2 * t3);
;             }
;             bf16x8 pf[2];
; #pragma unroll
;             for (int c = 0; c < 2; ++c) {
;                 const float basec = Rs * Gs[c] * (c == 0 ? Tt[1] : 1.f);
;                 float w[8];
; #pragma unroll
;                 for (int i = 0; i < 8; ++i) w[i] = be[c][i] * (suf[c][i] * basec);
;                 u32x4 pw; pw.x = cvt_pk_bf16(w[0], w[1]); pw.y = cvt_pk_bf16(w[2], w[3]); pw.z = cvt_pk_bf16(w[4], w[5]); pw.w = cvt_pk_bf16(w[6], w[7]);
;                 pf[c] = __builtin_bit_cast(bf16x8, pw);
;             }
;             Rs *= Tt[0] * Tt[1];
; #pragma unroll
;             for (int db = 0; db < 8; ++db)
; #pragma unroll
;                 for (int c = 0; c < 2; ++c) {
;                     const bf16x8 a = *(const LAS bf16x8*)(VL + (db * 16 + fr) * 144 + (32 * c + 8 * fq) * 2);
;                     o[db] = __builtin_amdgcn_mfma_f32_16x16x32_bf16(a, pf[c], o[db], 0, 0, 0);
;                 }
	v_cndmask_b32_e64 v120, v138, 1.0, s[0:1]
	v_mul_f32_e32 v121, v140, v159
	v_mul_f32_e32 v97, v120, v97
	ds_bpermute_b32 v120, v135, v121
	ds_bpermute_b32 v123, v118, v121
	ds_bpermute_b32 v122, v119, v121
	s_waitcnt lgkmcnt(3)
	v_cndmask_b32_e64 v124, 1.0, v139, s[4:5]
	v_mul_f32_e32 v124, v97, v124
	s_waitcnt lgkmcnt(2)
	v_cndmask_b32_e64 v97, 1.0, v120, s[10:11]
	s_waitcnt lgkmcnt(1)
	v_cndmask_b32_e64 v125, v123, 1.0, s[0:1]
	v_mul_f32_e32 v97, v125, v97
	s_waitcnt lgkmcnt(0)
	v_cndmask_b32_e64 v125, 1.0, v122, s[4:5]
	v_mul_f32_e32 v120, v120, v122
	v_mul_f32_e32 v121, v121, v123
	v_mul_f32_e32 v135, v97, v125
	v_mul_f32_e32 v140, v96, v124
	v_mul_f32_e32 v141, v120, v121
	v_mul_f32_e32 v97, v140, v141
	v_mul_f32_e32 v120, v103, v97
	v_mul_f32_e32 v101, v101, v120
	v_mul_f32_e32 v103, v142, v120
	v_mul_f32_e32 v120, v157, v97
	v_mul_f32_e32 v121, v143, v120
	v_mul_f32_e32 v120, v156, v97
	v_mul_f32_e32 v122, v144, v120
	v_mul_f32_e32 v120, v155, v97
	v_mul_f32_e32 v123, v145, v120
	v_mul_f32_e32 v120, v154, v97
	v_mul_f32_e32 v124, v146, v120
	v_mul_f32_e32 v120, v153, v97
	v_mul_f32_e32 v125, v126, v120
	v_mul_f32_e32 v120, v147, v97
	v_mul_f32_e32 v97, v127, v120
	v_cvt_pk_bf16_f32 v120, v101, v103
	v_cvt_pk_bf16_f32 v121, v121, v122
	v_cvt_pk_bf16_f32 v122, v123, v124
	v_cvt_pk_bf16_f32 v123, v125, v97
	v_mul_f32_e32 v97, v96, v135
	v_mul_f32_e32 v124, v97, v159
	v_mul_f32_e32 v101, v128, v124
	v_mul_f32_e32 v103, v129, v124
	v_mul_f32_e32 v124, v97, v158
	v_mul_f32_e32 v125, v130, v124
	v_mul_f32_e32 v124, v97, v148
	v_mul_f32_e32 v126, v131, v124
	v_mul_f32_e32 v124, v97, v149
	v_mul_f32_e32 v127, v132, v124
	v_mul_f32_e32 v124, v97, v150
	v_mul_f32_e32 v128, v133, v124
	v_mul_f32_e32 v124, v97, v152
	v_mul_f32_e32 v129, v134, v124
	v_mul_f32_e32 v124, v151, v97
	v_mul_f32_e32 v97, v99, v124
	v_cvt_pk_bf16_f32 v124, v101, v103
	v_cvt_pk_bf16_f32 v125, v125, v126
	v_cvt_pk_bf16_f32 v126, v127, v128
	v_cvt_pk_bf16_f32 v127, v129, v97
	ds_read_b128 v[128:131], v117 offset:17408
	ds_read_b128 v[132:135], v117 offset:17472
	s_waitcnt lgkmcnt(1)
	v_mfma_f32_16x16x32_bf16 v[60:63], v[128:131], v[120:123], v[60:63]
	ds_read_b128 v[128:131], v117 offset:19712
	s_waitcnt lgkmcnt(1)
	v_mfma_f32_16x16x32_bf16 v[60:63], v[132:135], v[124:127], v[60:63]
	ds_read_b128 v[132:135], v117 offset:19776
	s_waitcnt lgkmcnt(1)
	v_mfma_f32_16x16x32_bf16 v[72:75], v[128:131], v[120:123], v[72:75]
	ds_read_b128 v[128:131], v117 offset:22016
	s_waitcnt lgkmcnt(1)
	v_mfma_f32_16x16x32_bf16 v[72:75], v[132:135], v[124:127], v[72:75]
	ds_read_b128 v[132:135], v117 offset:22080
	s_waitcnt lgkmcnt(1)
	v_mfma_f32_16x16x32_bf16 v[56:59], v[128:131], v[120:123], v[56:59]
	ds_read_b128 v[128:131], v117 offset:24320
	s_waitcnt lgkmcnt(1)
	v_mfma_f32_16x16x32_bf16 v[56:59], v[132:135], v[124:127], v[56:59]
	ds_read_b128 v[132:135], v117 offset:24384
	s_waitcnt lgkmcnt(1)
	v_mfma_f32_16x16x32_bf16 v[44:47], v[128:131], v[120:123], v[44:47]
	ds_read_b128 v[128:131], v117 offset:26624
	s_waitcnt lgkmcnt(1)
	v_mfma_f32_16x16x32_bf16 v[44:47], v[132:135], v[124:127], v[44:47]
	ds_read_b128 v[132:135], v117 offset:26688
	s_waitcnt lgkmcnt(1)
	v_mfma_f32_16x16x32_bf16 v[32:35], v[128:131], v[120:123], v[32:35]
	ds_read_b128 v[128:131], v117 offset:28928
	s_waitcnt lgkmcnt(1)
	v_mfma_f32_16x16x32_bf16 v[32:35], v[132:135], v[124:127], v[32:35]
	ds_read_b128 v[132:135], v117 offset:28992
	s_waitcnt lgkmcnt(1)
	v_mfma_f32_16x16x32_bf16 v[24:27], v[128:131], v[120:123], v[24:27]
	ds_read_b128 v[128:131], v117 offset:31232
	s_waitcnt lgkmcnt(1)
	v_mfma_f32_16x16x32_bf16 v[24:27], v[132:135], v[124:127], v[24:27]
	ds_read_b128 v[132:135], v117 offset:31296
	s_waitcnt lgkmcnt(1)
	v_mfma_f32_16x16x32_bf16 v[20:23], v[128:131], v[120:123], v[20:23]
	ds_read_b128 v[128:131], v117 offset:33536
	s_waitcnt lgkmcnt(1)
	v_mfma_f32_16x16x32_bf16 v[20:23], v[132:135], v[124:127], v[20:23]
	ds_read_b128 v[132:135], v117 offset:33600
	s_waitcnt lgkmcnt(1)
	v_mfma_f32_16x16x32_bf16 v[16:19], v[128:131], v[120:123], v[16:19]
	v_mul_f32_e64 v120, v136, v138
	v_mul_f32_e64 v121, v137, v139
	v_mul_f32_e32 v97, v120, v121
	s_waitcnt lgkmcnt(0)
	v_mfma_f32_16x16x32_bf16 v[16:19], v[132:135], v[124:127], v[16:19]
	v_mul_f32_e32 v97, v97, v141
	v_mul_f32_e32 v96, v96, v97
